# MLA full interleave fast path without the s_sleep stagger
# speedup vs baseline: 1.0146x; 1.0051x over previous
; #define MFMA32(a, b, c) __builtin_amdgcn_mfma_f32_32x32x16_bf16((a), (b), (c), 0, 0, 0)
; #define AT_SB __builtin_amdgcn_sched_barrier(0);
; template <int DQK, int MODE, bool QN, bool KN> ...
;     ...
;   const int nsg = nkt >> 1;
;   auto tile_of = [&](int it) { return MODE == 2 ? (nkt - 1 - it) : it; };
;   auto stage_key0 = [&](int sg) { const int sc = sg < nsg ? sg : nsg - 1; return 128 * (MODE == 2 ? (nsg - 1 - sc) : sc); };
;   AT_GLOAD(rk0, rv0, 0)
;   AT_GLOAD(rk1, rv1, 1)
;   AT_SWRITE(rk0, rv0, 0)
;   __syncthreads();
;   auto compute = [&](int it, int bufi) {
;     const int kt = tile_of(it);
;     const int koff = (kt & 1) * 64;
;     const char* sK = smem + bufi * BUF + koff * KROW;
;     const char* sV = smem + bufi * BUF + KBYTES + koff * 64;
;     bool active = (MODE == 0) || (kt * 64 <= qwmax);
;     if (MODE == 2 && active) active = __builtin_amdgcn_ballot_w64(carry >= 1.17549435e-38f) != 0;
;     if (active) {
;       f32x16 sacc[2];
;       const float sinit = fixed_shift ? -sbound : 0.f;
; #pragma unroll
;       for (int kb = 0; kb < 2; ++kb) {
; #pragma unroll
;         for (int i = 0; i < 16; ++i) sacc[kb][i] = sinit;
; #pragma unroll
;         for (int s = 0; s < NS; ++s) {
;           const bf16x8 kf = *(const bf16x8*)(sK + (kb * 32 + r) * KROW + s * 32 + h * 16);
;           sacc[kb] = MFMA32(kf, qf[s], sacc[kb]);
;         }
;       }
;       const bool diag = (MODE != 0) && (kt * 64 + 63 >= q0 + wave * 32);
;       if (MODE != 0 && diag) {
; #pragma unroll
;         for (int kb = 0; kb < 2; ++kb)
; #pragma unroll
;           for (int i = 0; i < 16; ++i) {
;             const int key = kt * 64 + kb * 32 + (i & 3) + 8 * (i >> 2) + 4 * h;
;             if (MODE == 1 ? (key > qrow) : (key >= qrow)) sacc[kb][i] = -INFINITY;
;           }
;       }
;     ...
;   for (int sg = 0; sg < nsg; sg += 2) {
;     AT_SB AT_GLOAD(rk0, rv0, sg + 2)
;     AT_SB compute(2 * sg, 0); compute(2 * sg + 1, 0); AT_SB
;     AT_SWRITE(rk1, rv1, 1)
;     if (MODE == 2) { if (__syncthreads_and(carry < 1.17549435e-38f)) break; } else { __syncthreads(); }
;     AT_SB AT_GLOAD(rk1, rv1, sg + 3)
.LBB0_1197:
	s_or_b64 exec, exec, s[2:3]
	s_add_i32 s45, s45, 2
	s_addk_i32 s53, 0x100
	s_cmp_lt_u32 s55, s12
	s_waitcnt vmcnt(9)
	ds_write_b128 v244, v[2:5]
	s_waitcnt vmcnt(8)
	ds_write_b128 v245, v[6:9]
	s_waitcnt vmcnt(7)
	ds_write_b128 v246, v[10:13]
	s_waitcnt vmcnt(6)
	ds_write_b128 v248, v[204:207] offset:26624
	s_waitcnt vmcnt(5)
	ds_write_b128 v248, v[208:211] offset:30720
	s_waitcnt lgkmcnt(0)
	s_barrier
	s_cbranch_scc0 .LBB0_1166
.LBB0_1198:
	s_add_i32 s55, s45, -1
	s_min_i32 s2, s55, s13
	s_lshl_b32 s4, s2, 7
	v_add_u32_e32 v0, s4, v238
	v_mad_i64_i32 v[2:3], s[2:3], v0, s36, v[220:221]
	v_add_u32_e32 v0, s4, v239
	v_mad_i64_i32 v[6:7], s[2:3], v0, s36, v[222:223]
	v_add_u32_e32 v0, s4, v240
	v_mad_i64_i32 v[10:11], s[2:3], v0, s36, v[224:225]
	v_add_u32_e32 v0, s4, v241
	v_mad_i64_i32 v[14:15], s[2:3], v0, s37, v[218:219]
	v_add_u32_e32 v0, s4, v242
	global_load_dwordx4 v[2:5], v[2:3], off
	s_nop 0
	global_load_dwordx4 v[6:9], v[6:7], off
	s_nop 0
	global_load_dwordx4 v[10:13], v[10:11], off
	s_nop 0
	global_load_dwordx4 v[204:207], v[14:15], off
	v_mad_i64_i32 v[14:15], s[2:3], v0, s37, v[218:219]
	global_load_dwordx4 v[208:211], v[14:15], off
	s_add_i32 s2, s53, 0xffffff01
	v_cmp_le_i32_e32 vcc, s2, v243
	s_and_saveexec_b64 s[2:3], vcc
	s_cbranch_execz .LBB0_1208
	ds_read_b128 v[32:35], v251
	ds_read_b128 v[36:39], v251 offset:32
	ds_read_b128 v[40:43], v251 offset:64
	ds_read_b128 v[44:47], v251 offset:96
	ds_read_b128 v[48:51], v251 offset:128
	ds_read_b128 v[52:55], v251 offset:160
	ds_read_b128 v[112:115], v251 offset:6656
	ds_read_b128 v[116:119], v251 offset:6688
	ds_read_b128 v[120:123], v251 offset:6720
	ds_read_b128 v[124:127], v251 offset:6752
	ds_read_b128 v[144:147], v251 offset:6784
	ds_read_b128 v[148:151], v251 offset:6816
	s_add_i32 s4, s53, 0xffffff40
	v_cmp_ge_i32_e32 vcc, s4, v236
	s_waitcnt lgkmcnt(11)
	v_mfma_f32_32x32x16_bf16 v[80:95], v[32:35], v[160:163], v[16:31]
	s_waitcnt lgkmcnt(10)
	v_mfma_f32_32x32x16_bf16 v[80:95], v[36:39], v[164:167], v[80:95]
	s_waitcnt lgkmcnt(9)
	v_mfma_f32_32x32x16_bf16 v[80:95], v[40:43], v[168:171], v[80:95]
	s_waitcnt lgkmcnt(8)
	v_mfma_f32_32x32x16_bf16 v[80:95], v[44:47], v[172:175], v[80:95]
	s_waitcnt lgkmcnt(7)
	v_mfma_f32_32x32x16_bf16 v[80:95], v[48:51], v[176:179], v[80:95]
	s_waitcnt lgkmcnt(6)
	v_mfma_f32_32x32x16_bf16 v[80:95], v[52:55], v[180:183], v[80:95]
	s_or_b64 s[10:11], s[0:1], vcc
	s_cbranch_scc0 .Lmfp_0
	s_waitcnt lgkmcnt(5)
	v_mfma_f32_32x32x16_bf16 v[64:79], v[112:115], v[160:163], v[16:31]
	s_waitcnt lgkmcnt(4)
	v_mfma_f32_32x32x16_bf16 v[64:79], v[116:119], v[164:167], v[64:79]
	s_waitcnt lgkmcnt(3)
	v_mfma_f32_32x32x16_bf16 v[64:79], v[120:123], v[168:171], v[64:79]
	s_waitcnt lgkmcnt(2)
	v_mfma_f32_32x32x16_bf16 v[64:79], v[124:127], v[172:175], v[64:79]
	s_waitcnt lgkmcnt(1)
	v_mfma_f32_32x32x16_bf16 v[64:79], v[144:147], v[176:179], v[64:79]
	s_waitcnt lgkmcnt(0)
	v_mfma_f32_32x32x16_bf16 v[64:79], v[148:151], v[180:183], v[64:79]
	s_and_saveexec_b64 s[10:11], vcc
	s_cbranch_execz .LBB0_1201
	v_add_u32_e32 v0, s53, v247
	v_add_u32_e32 v14, 0xffffff01, v0
	v_cmp_lt_i32_e32 vcc, v14, v237
	s_nop 1
	v_cndmask_b32_e32 v81, v234, v81, vcc
	v_cmp_le_i32_e32 vcc, v14, v237
	v_add_u32_e32 v14, 0xffffff03, v0
	s_nop 0
	v_cndmask_b32_e32 v80, v234, v80, vcc
	v_cmp_le_i32_e32 vcc, v14, v237
	v_add_u32_e32 v14, 0xffffff04, v0
	s_nop 0
	v_cndmask_b32_e32 v82, v234, v82, vcc
	v_cmp_le_i32_e32 vcc, v14, v237
	v_add_u32_e32 v14, 0xffffff09, v0
	s_nop 0
	v_cndmask_b32_e32 v83, v234, v83, vcc
	v_cmp_le_i32_e32 vcc, v14, v237
	v_add_u32_e32 v14, 0xffffff0a, v0
	s_nop 0
	v_cndmask_b32_e32 v84, v234, v84, vcc
	v_cmp_le_i32_e32 vcc, v14, v237
	v_add_u32_e32 v14, 0xffffff0b, v0
	s_nop 0
	v_cndmask_b32_e32 v85, v234, v85, vcc
	v_cmp_le_i32_e32 vcc, v14, v237
	v_add_u32_e32 v14, 0xffffff0c, v0
	s_nop 0
	v_cndmask_b32_e32 v86, v234, v86, vcc
	v_cmp_le_i32_e32 vcc, v14, v237
	v_add_u32_e32 v14, 0xffffff11, v0
	s_nop 0
	v_cndmask_b32_e32 v87, v234, v87, vcc
	v_cmp_le_i32_e32 vcc, v14, v237
	v_add_u32_e32 v14, 0xffffff12, v0
	s_nop 0
	v_cndmask_b32_e32 v88, v234, v88, vcc
	v_cmp_le_i32_e32 vcc, v14, v237
	v_add_u32_e32 v14, 0xffffff13, v0
	s_nop 0
	v_cndmask_b32_e32 v89, v234, v89, vcc
	v_cmp_le_i32_e32 vcc, v14, v237
	v_add_u32_e32 v14, 0xffffff14, v0
	s_nop 0
	v_cndmask_b32_e32 v90, v234, v90, vcc
	v_cmp_le_i32_e32 vcc, v14, v237
	v_add_u32_e32 v14, 0xffffff19, v0
	s_nop 0
	v_cndmask_b32_e32 v91, v234, v91, vcc
	v_cmp_le_i32_e32 vcc, v14, v237
	v_add_u32_e32 v14, 0xffffff1a, v0
	s_nop 0
	v_cndmask_b32_e32 v92, v234, v92, vcc
	v_cmp_le_i32_e32 vcc, v14, v237
	v_add_u32_e32 v14, 0xffffff1b, v0
	s_nop 0
	v_cndmask_b32_e32 v93, v234, v93, vcc
	v_cmp_le_i32_e32 vcc, v14, v237
	v_add_u32_e32 v14, 0xffffff1c, v0
	s_nop 0
	v_cndmask_b32_e32 v94, v234, v94, vcc
	v_cmp_le_i32_e32 vcc, v14, v237
	v_add_u32_e32 v14, 0xffffff21, v0
	s_nop 0
	v_cndmask_b32_e32 v95, v234, v95, vcc
	v_cmp_le_i32_e32 vcc, v14, v237
	v_add_u32_e32 v14, 0xffffff22, v0
	s_nop 0
	v_cndmask_b32_e32 v64, v234, v64, vcc
	v_cmp_le_i32_e32 vcc, v14, v237
	v_add_u32_e32 v14, 0xffffff23, v0
	s_nop 0
	v_cndmask_b32_e32 v65, v234, v65, vcc
	v_cmp_le_i32_e32 vcc, v14, v237
	v_add_u32_e32 v14, 0xffffff24, v0
	s_nop 0
	v_cndmask_b32_e32 v66, v234, v66, vcc
	v_cmp_le_i32_e32 vcc, v14, v237
	v_add_u32_e32 v14, 0xffffff29, v0
	s_nop 0
	v_cndmask_b32_e32 v67, v234, v67, vcc
	v_cmp_le_i32_e32 vcc, v14, v237
	v_add_u32_e32 v14, 0xffffff2a, v0
	s_nop 0
	v_cndmask_b32_e32 v68, v234, v68, vcc
	v_cmp_le_i32_e32 vcc, v14, v237
	v_add_u32_e32 v14, 0xffffff2b, v0
	s_nop 0
	v_cndmask_b32_e32 v69, v234, v69, vcc
	v_cmp_le_i32_e32 vcc, v14, v237
	v_add_u32_e32 v14, 0xffffff2c, v0
	s_nop 0
	v_cndmask_b32_e32 v70, v234, v70, vcc
	v_cmp_le_i32_e32 vcc, v14, v237
	v_add_u32_e32 v14, 0xffffff31, v0
	s_nop 0
	v_cndmask_b32_e32 v71, v234, v71, vcc
	v_cmp_le_i32_e32 vcc, v14, v237
	v_add_u32_e32 v14, 0xffffff32, v0
	s_nop 0
	v_cndmask_b32_e32 v72, v234, v72, vcc
	v_cmp_le_i32_e32 vcc, v14, v237
	v_add_u32_e32 v14, 0xffffff33, v0
	s_nop 0
	v_cndmask_b32_e32 v73, v234, v73, vcc
	v_cmp_le_i32_e32 vcc, v14, v237
	v_add_u32_e32 v14, 0xffffff34, v0
	s_nop 0
	v_cndmask_b32_e32 v74, v234, v74, vcc
	v_cmp_le_i32_e32 vcc, v14, v237
	v_add_u32_e32 v14, 0xffffff39, v0
	s_nop 0
	v_cndmask_b32_e32 v75, v234, v75, vcc
	v_cmp_le_i32_e32 vcc, v14, v237
	v_add_u32_e32 v14, 0xffffff3a, v0
	s_nop 0
	v_cndmask_b32_e32 v76, v234, v76, vcc
	v_cmp_le_i32_e32 vcc, v14, v237
	v_add_u32_e32 v14, 0xffffff3b, v0
	v_add_u32_e32 v0, 0xffffff3c, v0
	v_cndmask_b32_e32 v77, v234, v77, vcc
	v_cmp_le_i32_e32 vcc, v14, v237
	s_nop 1
	v_cndmask_b32_e32 v78, v234, v78, vcc
	v_cmp_le_i32_e32 vcc, v0, v237
	s_nop 1
	v_cndmask_b32_e32 v79, v234, v79, vcc

; #define MFMA32(a, b, c) __builtin_amdgcn_mfma_f32_32x32x16_bf16((a), (b), (c), 0, 0, 0)
; #define AT_SB __builtin_amdgcn_sched_barrier(0);
; template <int DQK, int MODE, bool QN, bool KN> ...
;     ...
;   const int nsg = nkt >> 1;
;   auto tile_of = [&](int it) { return MODE == 2 ? (nkt - 1 - it) : it; };
;   auto stage_key0 = [&](int sg) { const int sc = sg < nsg ? sg : nsg - 1; return 128 * (MODE == 2 ? (nsg - 1 - sc) : sc); };
;   AT_GLOAD(rk0, rv0, 0)
;   AT_GLOAD(rk1, rv1, 1)
;   AT_SWRITE(rk0, rv0, 0)
;   __syncthreads();
;   auto compute = [&](int it, int bufi) {
;     const int kt = tile_of(it);
;     const int koff = (kt & 1) * 64;
;     const char* sK = smem + bufi * BUF + koff * KROW;
;     const char* sV = smem + bufi * BUF + KBYTES + koff * 64;
;     bool active = (MODE == 0) || (kt * 64 <= qwmax);
;     if (MODE == 2 && active) active = __builtin_amdgcn_ballot_w64(carry >= 1.17549435e-38f) != 0;
;     if (active) {
;       f32x16 sacc[2];
;       const float sinit = fixed_shift ? -sbound : 0.f;
; #pragma unroll
;       for (int kb = 0; kb < 2; ++kb) {
; #pragma unroll
;         for (int i = 0; i < 16; ++i) sacc[kb][i] = sinit;
; #pragma unroll
;         for (int s = 0; s < NS; ++s) {
;           const bf16x8 kf = *(const bf16x8*)(sK + (kb * 32 + r) * KROW + s * 32 + h * 16);
;           sacc[kb] = MFMA32(kf, qf[s], sacc[kb]);
;         }
;       }
;       const bool diag = (MODE != 0) && (kt * 64 + 63 >= q0 + wave * 32);
;       if (MODE != 0 && diag) {
; #pragma unroll
;         for (int kb = 0; kb < 2; ++kb)
; #pragma unroll
;           for (int i = 0; i < 16; ++i) {
;             const int key = kt * 64 + kb * 32 + (i & 3) + 8 * (i >> 2) + 4 * h;
;             if (MODE == 1 ? (key > qrow) : (key >= qrow)) sacc[kb][i] = -INFINITY;
;           }
;       }
;     ...
;   for (int sg = 0; sg < nsg; sg += 2) {
;     AT_SB AT_GLOAD(rk0, rv0, sg + 2)
;     AT_SB compute(2 * sg, 0); compute(2 * sg + 1, 0); AT_SB
;     AT_SWRITE(rk1, rv1, 1)
;     if (MODE == 2) { if (__syncthreads_and(carry < 1.17549435e-38f)) break; } else { __syncthreads(); }
;     AT_SB AT_GLOAD(rk1, rv1, sg + 3)
;     AT_SB compute(2 * sg + 2, 1); compute(2 * sg + 3, 1); AT_SB
;     AT_SWRITE(rk0, rv0, 0)
;     if (MODE == 2) { if (__syncthreads_and(carry < 1.17549435e-38f)) break; } else { __syncthreads(); }
.LBB0_1218:
	s_or_b64 exec, exec, s[2:3]
	s_waitcnt vmcnt(9)
	ds_write_b128 v244, v[184:187] offset:43008
	s_waitcnt vmcnt(8)
	ds_write_b128 v245, v[188:191] offset:43008
	s_waitcnt vmcnt(7)
	ds_write_b128 v246, v[192:195] offset:43008
	s_waitcnt vmcnt(6)
	ds_write_b128 v250, v[196:199]
	s_waitcnt vmcnt(5)
	ds_write_b128 v250, v[200:203] offset:4096
	s_waitcnt lgkmcnt(0)
	s_barrier
	s_min_i32 s2, s45, s13
	s_lshl_b32 s4, s2, 7
	v_add_u32_e32 v0, s4, v238
	v_mad_i64_i32 v[14:15], s[2:3], v0, s36, v[220:221]
	v_add_u32_e32 v0, s4, v239
	v_mad_i64_i32 v[64:65], s[2:3], v0, s36, v[222:223]
	v_add_u32_e32 v0, s4, v240
	global_load_dwordx4 v[184:187], v[14:15], off
	global_load_dwordx4 v[188:191], v[64:65], off
	v_mad_i64_i32 v[14:15], s[2:3], v0, s36, v[224:225]
	v_add_u32_e32 v0, s4, v241
	v_mad_i64_i32 v[64:65], s[2:3], v0, s37, v[218:219]
	v_add_u32_e32 v0, s4, v242
	global_load_dwordx4 v[192:195], v[14:15], off
	global_load_dwordx4 v[196:199], v[64:65], off
	v_mad_i64_i32 v[14:15], s[2:3], v0, s37, v[218:219]
	global_load_dwordx4 v[200:203], v[14:15], off
	s_add_i32 s2, s53, 0xffffff81
	v_cmp_le_i32_e32 vcc, s2, v243
	s_and_saveexec_b64 s[2:3], vcc
	s_cbranch_execz .LBB0_1228
	ds_read_b128 v[32:35], v251 offset:43008
	ds_read_b128 v[36:39], v251 offset:43040
	ds_read_b128 v[40:43], v251 offset:43072
	ds_read_b128 v[44:47], v251 offset:43104
	ds_read_b128 v[48:51], v251 offset:43136
	ds_read_b128 v[52:55], v251 offset:43168
	ds_read_b128 v[112:115], v251 offset:49664
	ds_read_b128 v[116:119], v251 offset:49696
	ds_read_b128 v[120:123], v251 offset:49728
	ds_read_b128 v[124:127], v251 offset:49760
	ds_read_b128 v[144:147], v251 offset:49792
	ds_read_b128 v[148:151], v251 offset:49824
	s_sub_i32 s4, s53, 64
	v_cmp_ge_i32_e32 vcc, s4, v236
	s_waitcnt lgkmcnt(11)
	v_mfma_f32_32x32x16_bf16 v[80:95], v[32:35], v[160:163], v[16:31]
	s_waitcnt lgkmcnt(10)
	v_mfma_f32_32x32x16_bf16 v[80:95], v[36:39], v[164:167], v[80:95]
	s_waitcnt lgkmcnt(9)
	v_mfma_f32_32x32x16_bf16 v[80:95], v[40:43], v[168:171], v[80:95]
	s_waitcnt lgkmcnt(8)
	v_mfma_f32_32x32x16_bf16 v[80:95], v[44:47], v[172:175], v[80:95]
	s_waitcnt lgkmcnt(7)
	v_mfma_f32_32x32x16_bf16 v[80:95], v[48:51], v[176:179], v[80:95]
	s_waitcnt lgkmcnt(6)
	v_mfma_f32_32x32x16_bf16 v[80:95], v[52:55], v[180:183], v[80:95]
	s_or_b64 s[10:11], s[0:1], vcc
	s_cbranch_scc0 .Lmfp_2
	s_waitcnt lgkmcnt(5)
	v_mfma_f32_32x32x16_bf16 v[64:79], v[112:115], v[160:163], v[16:31]
	s_waitcnt lgkmcnt(4)
	v_mfma_f32_32x32x16_bf16 v[64:79], v[116:119], v[164:167], v[64:79]
	s_waitcnt lgkmcnt(3)
	v_mfma_f32_32x32x16_bf16 v[64:79], v[120:123], v[168:171], v[64:79]
	s_waitcnt lgkmcnt(2)
	v_mfma_f32_32x32x16_bf16 v[64:79], v[124:127], v[172:175], v[64:79]
	s_waitcnt lgkmcnt(1)
	v_mfma_f32_32x32x16_bf16 v[64:79], v[144:147], v[176:179], v[64:79]
	s_waitcnt lgkmcnt(0)
	v_mfma_f32_32x32x16_bf16 v[64:79], v[148:151], v[180:183], v[64:79]
	s_and_saveexec_b64 s[10:11], vcc
	s_cbranch_execz .LBB0_1221
	v_add_u32_e32 v0, s53, v247
	v_add_u32_e32 v14, 0xffffff81, v0
	v_cmp_le_i32_e32 vcc, v14, v237
	v_add_u32_e32 v14, 0xffffff82, v0
	s_nop 0
	v_cndmask_b32_e32 v80, v234, v80, vcc
	v_cmp_le_i32_e32 vcc, v14, v237
	v_add_u32_e32 v14, 0xffffff83, v0
	s_nop 0
	v_cndmask_b32_e32 v81, v234, v81, vcc
	v_cmp_le_i32_e32 vcc, v14, v237
	v_add_u32_e32 v14, 0xffffff84, v0
	s_nop 0
	v_cndmask_b32_e32 v82, v234, v82, vcc
	v_cmp_le_i32_e32 vcc, v14, v237
	v_add_u32_e32 v14, 0xffffff89, v0
	s_nop 0
	v_cndmask_b32_e32 v83, v234, v83, vcc
	v_cmp_le_i32_e32 vcc, v14, v237
	v_add_u32_e32 v14, 0xffffff8a, v0
	s_nop 0
	v_cndmask_b32_e32 v84, v234, v84, vcc
	v_cmp_le_i32_e32 vcc, v14, v237
	v_add_u32_e32 v14, 0xffffff8b, v0
	s_nop 0
	v_cndmask_b32_e32 v85, v234, v85, vcc
	v_cmp_le_i32_e32 vcc, v14, v237
	v_add_u32_e32 v14, 0xffffff8c, v0
	s_nop 0
	v_cndmask_b32_e32 v86, v234, v86, vcc
	v_cmp_le_i32_e32 vcc, v14, v237
	v_add_u32_e32 v14, 0xffffff91, v0
	s_nop 0
	v_cndmask_b32_e32 v87, v234, v87, vcc
	v_cmp_le_i32_e32 vcc, v14, v237
	v_add_u32_e32 v14, 0xffffff92, v0
	s_nop 0
	v_cndmask_b32_e32 v88, v234, v88, vcc
	v_cmp_le_i32_e32 vcc, v14, v237
	v_add_u32_e32 v14, 0xffffff93, v0
	s_nop 0
	v_cndmask_b32_e32 v89, v234, v89, vcc
	v_cmp_le_i32_e32 vcc, v14, v237
	v_add_u32_e32 v14, 0xffffff94, v0
	s_nop 0
	v_cndmask_b32_e32 v90, v234, v90, vcc
	v_cmp_le_i32_e32 vcc, v14, v237
	v_add_u32_e32 v14, 0xffffff99, v0
	s_nop 0
	v_cndmask_b32_e32 v91, v234, v91, vcc
	v_cmp_le_i32_e32 vcc, v14, v237
	v_add_u32_e32 v14, 0xffffff9a, v0
	s_nop 0
	v_cndmask_b32_e32 v92, v234, v92, vcc
	v_cmp_le_i32_e32 vcc, v14, v237
	v_add_u32_e32 v14, 0xffffff9b, v0
	s_nop 0
	v_cndmask_b32_e32 v93, v234, v93, vcc
	v_cmp_le_i32_e32 vcc, v14, v237
	v_add_u32_e32 v14, 0xffffff9c, v0
	s_nop 0
	v_cndmask_b32_e32 v94, v234, v94, vcc
	v_cmp_le_i32_e32 vcc, v14, v237
	v_add_u32_e32 v14, 0xffffffa1, v0
	s_nop 0
	v_cndmask_b32_e32 v95, v234, v95, vcc
	v_cmp_le_i32_e32 vcc, v14, v237
	v_add_u32_e32 v14, 0xffffffa2, v0
	s_nop 0
	v_cndmask_b32_e32 v64, v234, v64, vcc
	v_cmp_le_i32_e32 vcc, v14, v237
	v_add_u32_e32 v14, 0xffffffa3, v0
	s_nop 0
	v_cndmask_b32_e32 v65, v234, v65, vcc
	v_cmp_le_i32_e32 vcc, v14, v237
	v_add_u32_e32 v14, 0xffffffa4, v0
	s_nop 0
	v_cndmask_b32_e32 v66, v234, v66, vcc
	v_cmp_le_i32_e32 vcc, v14, v237
	v_add_u32_e32 v14, 0xffffffa9, v0
	s_nop 0
	v_cndmask_b32_e32 v67, v234, v67, vcc
	v_cmp_le_i32_e32 vcc, v14, v237
	v_add_u32_e32 v14, 0xffffffaa, v0
	s_nop 0
	v_cndmask_b32_e32 v68, v234, v68, vcc
	v_cmp_le_i32_e32 vcc, v14, v237
	v_add_u32_e32 v14, 0xffffffab, v0
	s_nop 0
	v_cndmask_b32_e32 v69, v234, v69, vcc
	v_cmp_le_i32_e32 vcc, v14, v237
	v_add_u32_e32 v14, 0xffffffac, v0
	s_nop 0
	v_cndmask_b32_e32 v70, v234, v70, vcc
	v_cmp_le_i32_e32 vcc, v14, v237
	v_add_u32_e32 v14, 0xffffffb1, v0
	s_nop 0
	v_cndmask_b32_e32 v71, v234, v71, vcc
	v_cmp_le_i32_e32 vcc, v14, v237
	v_add_u32_e32 v14, 0xffffffb2, v0
	s_nop 0
	v_cndmask_b32_e32 v72, v234, v72, vcc
	v_cmp_le_i32_e32 vcc, v14, v237
	v_add_u32_e32 v14, 0xffffffb3, v0
	s_nop 0
	v_cndmask_b32_e32 v73, v234, v73, vcc
	v_cmp_le_i32_e32 vcc, v14, v237
	v_add_u32_e32 v14, 0xffffffb4, v0
	s_nop 0
	v_cndmask_b32_e32 v74, v234, v74, vcc
	v_cmp_le_i32_e32 vcc, v14, v237
	v_add_u32_e32 v14, 0xffffffb9, v0
	s_nop 0
	v_cndmask_b32_e32 v75, v234, v75, vcc
	v_cmp_le_i32_e32 vcc, v14, v237
	v_add_u32_e32 v14, 0xffffffba, v0
	s_nop 0
	v_cndmask_b32_e32 v76, v234, v76, vcc
	v_cmp_le_i32_e32 vcc, v14, v237
	v_add_u32_e32 v14, 0xffffffbb, v0
	v_add_u32_e32 v0, 0xffffffbc, v0
	v_cndmask_b32_e32 v77, v234, v77, vcc
	v_cmp_le_i32_e32 vcc, v14, v237
	s_nop 1
	v_cndmask_b32_e32 v78, v234, v78, vcc
	v_cmp_le_i32_e32 vcc, v0, v237
	s_nop 1
	v_cndmask_b32_e32 v79, v234, v79, vcc
